# prologue conversion stores also write-through (sc1)
# baseline (speedup 1.0000x reference)
; __device__ __forceinline__ unsigned pkbf(float lo, float hi) { typedef float f2_t __attribute__((ext_vector_type(2))); typedef __bf16 b2_t __attribute__((ext_vector_type(2))); f2_t v = {lo, hi}; b2_t b = __builtin_convertvector(v, b2_t); return __builtin_bit_cast(unsigned, b); }
; __device__ __forceinline__ void transpose_item(const float* W, int K, int N, bf16* WT, int k0, int n0, int dst_row0, const float* gain_k0, float* scr, int lane) {
;     ...
; #pragma unroll
;     for (int j = 0; j < 8; ++j) { const int n = (lane >> 3) + 8 * j; const float* s = scr + (8 * c) * 65 + n;
;         u32x4 o; o.x = pkbf(s[0 * 65] * g0.x, s[1 * 65] * g0.y); o.y = pkbf(s[2 * 65] * g0.z, s[3 * 65] * g0.w); o.z = pkbf(s[4 * 65] * g1.x, s[5 * 65] * g1.y); o.w = pkbf(s[6 * 65] * g1.z, s[7 * 65] * g1.w);
;         *(u32x4*)(WT + (size_t)(dst_row0 + n) * K + k0 + 8 * c) = o; }
;     asm volatile("s_waitcnt lgkmcnt(0)" ::: "memory");
.LBB0_9:
	ds_read2_b32 v[64:65], v20 offset1:8
	ds_read2_b32 v[66:67], v20 offset0:65 offset1:73
	ds_read2_b32 v[68:69], v20 offset0:130 offset1:138
	ds_read2_b32 v[70:71], v20 offset0:195 offset1:203
	ds_read2_b32 v[72:73], v58 offset0:4 offset1:12
	ds_read2_b32 v[74:75], v58 offset0:69 offset1:77
	ds_read2_b32 v[76:77], v58 offset0:134 offset1:142
	ds_read2_b32 v[78:79], v58 offset0:199 offset1:207
	s_waitcnt lgkmcnt(7)
	v_mov_b32_e32 v60, v64
	s_waitcnt lgkmcnt(6)
	v_mov_b32_e32 v61, v66
	s_waitcnt lgkmcnt(5)
	v_mov_b32_e32 v62, v68
	s_waitcnt lgkmcnt(4)
	v_mov_b32_e32 v63, v70
	s_mul_hi_i32 s0, s8, 0xe00000
	s_mul_i32 s8, s8, 0xe00000
	s_waitcnt vmcnt(1)
	v_pk_mul_f32 v[60:61], v[2:3], v[60:61]
	v_pk_mul_f32 v[62:63], v[4:5], v[62:63]
	s_add_u32 s11, s26, s8
	v_cvt_pk_bf16_f32 v60, v60, v61
	v_cvt_pk_bf16_f32 v61, v62, v63
	s_waitcnt lgkmcnt(3)
	v_mov_b32_e32 v62, v72
	s_waitcnt lgkmcnt(2)
	v_mov_b32_e32 v63, v74
	s_waitcnt lgkmcnt(1)
	v_mov_b32_e32 v80, v76
	s_waitcnt lgkmcnt(0)
	v_mov_b32_e32 v81, v78
	s_addc_u32 s0, s27, s0
	s_lshl_b64 s[8:9], s[12:13], 1
	s_waitcnt vmcnt(0)
	v_pk_mul_f32 v[62:63], v[6:7], v[62:63]
	v_pk_mul_f32 v[80:81], v[8:9], v[80:81]
	s_add_u32 s8, s11, s8
	v_cvt_pk_bf16_f32 v62, v62, v63
	v_cvt_pk_bf16_f32 v63, v80, v81
	v_or_b32_e32 v80, s10, v19
	s_addc_u32 s9, s0, s9
	v_mov_b32_e32 v15, v11
	v_ashrrev_i32_e32 v81, 31, v80
	v_lshl_add_u64 v[16:17], s[8:9], 0, v[14:15]
	v_lshlrev_b64 v[80:81], 12, v[80:81]
	v_lshl_add_u64 v[80:81], v[16:17], 0, v[80:81]
	v_mov_b32_e32 v66, v65
	v_mov_b32_e32 v70, v69
	global_store_dwordx4 v[80:81], v[60:63], off sc1
	v_mov_b32_e32 v74, v73
	v_mov_b32_e32 v78, v77
	v_pk_mul_f32 v[60:61], v[2:3], v[66:67]
	v_pk_mul_f32 v[62:63], v[4:5], v[70:71]
	v_cvt_pk_bf16_f32 v60, v60, v61
	v_cvt_pk_bf16_f32 v61, v62, v63
	v_pk_mul_f32 v[62:63], v[6:7], v[74:75]
	v_pk_mul_f32 v[64:65], v[8:9], v[78:79]
	v_cvt_pk_bf16_f32 v62, v62, v63
	v_cvt_pk_bf16_f32 v63, v64, v65
	v_or_b32_e32 v64, s10, v21
	v_ashrrev_i32_e32 v65, 31, v64
	v_lshlrev_b64 v[64:65], 12, v[64:65]
	v_lshl_add_u64 v[64:65], v[16:17], 0, v[64:65]
	ds_read2_b32 v[66:67], v20 offset0:16 offset1:24
	ds_read2_b32 v[68:69], v20 offset0:81 offset1:89
	global_store_dwordx4 v[64:65], v[60:63], off sc1
	ds_read2_b32 v[64:65], v20 offset0:146 offset1:154
	ds_read2_b32 v[70:71], v20 offset0:211 offset1:219
	ds_read2_b32 v[72:73], v58 offset0:20 offset1:28
	ds_read2_b32 v[74:75], v58 offset0:85 offset1:93
	ds_read2_b32 v[76:77], v58 offset0:150 offset1:158
	ds_read2_b32 v[78:79], v58 offset0:215 offset1:223
	s_waitcnt lgkmcnt(7)
	v_mov_b32_e32 v60, v66
	s_waitcnt lgkmcnt(6)
	v_mov_b32_e32 v61, v68
	s_waitcnt lgkmcnt(5)
	v_mov_b32_e32 v62, v64
	s_waitcnt lgkmcnt(4)
	v_mov_b32_e32 v63, v70
	v_pk_mul_f32 v[60:61], v[2:3], v[60:61]
	v_pk_mul_f32 v[62:63], v[4:5], v[62:63]
	v_cvt_pk_bf16_f32 v60, v60, v61
	v_cvt_pk_bf16_f32 v61, v62, v63
	s_waitcnt lgkmcnt(3)
	v_mov_b32_e32 v62, v72
	s_waitcnt lgkmcnt(2)
	v_mov_b32_e32 v63, v74
	s_waitcnt lgkmcnt(1)
	v_mov_b32_e32 v80, v76
	s_waitcnt lgkmcnt(0)
	v_mov_b32_e32 v81, v78
	v_pk_mul_f32 v[62:63], v[6:7], v[62:63]
	v_pk_mul_f32 v[80:81], v[8:9], v[80:81]
	v_cvt_pk_bf16_f32 v62, v62, v63
	v_cvt_pk_bf16_f32 v63, v80, v81
	v_or_b32_e32 v80, s10, v22
	v_ashrrev_i32_e32 v81, 31, v80
	v_lshlrev_b64 v[80:81], 12, v[80:81]
	v_lshl_add_u64 v[80:81], v[16:17], 0, v[80:81]
	v_mov_b32_e32 v68, v67
	v_mov_b32_e32 v70, v65
	global_store_dwordx4 v[80:81], v[60:63], off sc1
	v_mov_b32_e32 v74, v73
	v_mov_b32_e32 v78, v77
	v_pk_mul_f32 v[60:61], v[2:3], v[68:69]
	v_pk_mul_f32 v[62:63], v[4:5], v[70:71]
	v_cvt_pk_bf16_f32 v60, v60, v61
	v_cvt_pk_bf16_f32 v61, v62, v63
	v_pk_mul_f32 v[62:63], v[6:7], v[74:75]
	v_pk_mul_f32 v[64:65], v[8:9], v[78:79]
	v_cvt_pk_bf16_f32 v62, v62, v63
	v_cvt_pk_bf16_f32 v63, v64, v65
	v_or_b32_e32 v64, s10, v23
	v_ashrrev_i32_e32 v65, 31, v64
	v_lshlrev_b64 v[64:65], 12, v[64:65]
	v_lshl_add_u64 v[64:65], v[16:17], 0, v[64:65]
	ds_read2_b32 v[66:67], v20 offset0:32 offset1:40
	ds_read2_b32 v[68:69], v20 offset0:97 offset1:105
	global_store_dwordx4 v[64:65], v[60:63], off sc1
	ds_read2_b32 v[64:65], v20 offset0:162 offset1:170
	ds_read2_b32 v[70:71], v20 offset0:227 offset1:235
	ds_read2_b32 v[72:73], v58 offset0:36 offset1:44
	ds_read2_b32 v[74:75], v58 offset0:101 offset1:109
	ds_read2_b32 v[76:77], v58 offset0:166 offset1:174
	ds_read2_b32 v[78:79], v58 offset0:231 offset1:239
	s_waitcnt lgkmcnt(7)
; __device__ __forceinline__ unsigned pkbf(float lo, float hi) { typedef float f2_t __attribute__((ext_vector_type(2))); typedef __bf16 b2_t __attribute__((ext_vector_type(2))); f2_t v = {lo, hi}; b2_t b = __builtin_convertvector(v, b2_t); return __builtin_bit_cast(unsigned, b); }
; __device__ __forceinline__ void transpose_item(const float* W, int K, int N, bf16* WT, int k0, int n0, int dst_row0, const float* gain_k0, float* scr, int lane) {
;     ...
; #pragma unroll
;     for (int j = 0; j < 8; ++j) { const int n = (lane >> 3) + 8 * j; const float* s = scr + (8 * c) * 65 + n;
;         u32x4 o; o.x = pkbf(s[0 * 65] * g0.x, s[1 * 65] * g0.y); o.y = pkbf(s[2 * 65] * g0.z, s[3 * 65] * g0.w); o.z = pkbf(s[4 * 65] * g1.x, s[5 * 65] * g1.y); o.w = pkbf(s[6 * 65] * g1.z, s[7 * 65] * g1.w);
;         *(u32x4*)(WT + (size_t)(dst_row0 + n) * K + k0 + 8 * c) = o; }
;     asm volatile("s_waitcnt lgkmcnt(0)" ::: "memory");
	v_mov_b32_e32 v60, v66
	s_waitcnt lgkmcnt(6)
	v_mov_b32_e32 v61, v68
	s_waitcnt lgkmcnt(5)
	v_mov_b32_e32 v62, v64
	s_waitcnt lgkmcnt(4)
	v_mov_b32_e32 v63, v70
	v_pk_mul_f32 v[60:61], v[2:3], v[60:61]
	v_pk_mul_f32 v[62:63], v[4:5], v[62:63]
	v_cvt_pk_bf16_f32 v60, v60, v61
	v_cvt_pk_bf16_f32 v61, v62, v63
	s_waitcnt lgkmcnt(3)
	v_mov_b32_e32 v62, v72
	s_waitcnt lgkmcnt(2)
	v_mov_b32_e32 v63, v74
	s_waitcnt lgkmcnt(1)
	v_mov_b32_e32 v80, v76
	s_waitcnt lgkmcnt(0)
	v_mov_b32_e32 v81, v78
	v_pk_mul_f32 v[62:63], v[6:7], v[62:63]
	v_pk_mul_f32 v[80:81], v[8:9], v[80:81]
	v_cvt_pk_bf16_f32 v62, v62, v63
	v_cvt_pk_bf16_f32 v63, v80, v81
	v_or_b32_e32 v80, s10, v24
	v_ashrrev_i32_e32 v81, 31, v80
	v_lshlrev_b64 v[80:81], 12, v[80:81]
	v_lshl_add_u64 v[80:81], v[16:17], 0, v[80:81]
	v_mov_b32_e32 v68, v67
	v_mov_b32_e32 v70, v65
	global_store_dwordx4 v[80:81], v[60:63], off sc1
	v_mov_b32_e32 v74, v73
	v_mov_b32_e32 v78, v77
	v_pk_mul_f32 v[60:61], v[2:3], v[68:69]
	v_pk_mul_f32 v[62:63], v[4:5], v[70:71]
	v_cvt_pk_bf16_f32 v60, v60, v61
	v_cvt_pk_bf16_f32 v61, v62, v63
	v_pk_mul_f32 v[62:63], v[6:7], v[74:75]
	v_pk_mul_f32 v[64:65], v[8:9], v[78:79]
	v_cvt_pk_bf16_f32 v62, v62, v63
	v_cvt_pk_bf16_f32 v63, v64, v65
	v_or_b32_e32 v64, s10, v25
	v_ashrrev_i32_e32 v65, 31, v64
	v_lshlrev_b64 v[64:65], 12, v[64:65]
	v_lshl_add_u64 v[64:65], v[16:17], 0, v[64:65]
	ds_read2_b32 v[66:67], v20 offset0:48 offset1:56
	ds_read2_b32 v[68:69], v20 offset0:113 offset1:121
	global_store_dwordx4 v[64:65], v[60:63], off sc1
	ds_read2_b32 v[64:65], v20 offset0:178 offset1:186
	ds_read2_b32 v[70:71], v20 offset0:243 offset1:251
	ds_read2_b32 v[72:73], v58 offset0:52 offset1:60
	ds_read2_b32 v[74:75], v58 offset0:117 offset1:125
	ds_read2_b32 v[76:77], v58 offset0:182 offset1:190
	ds_read2_b32 v[78:79], v58 offset0:247 offset1:255
	s_waitcnt lgkmcnt(7)
	v_mov_b32_e32 v60, v66
	s_waitcnt lgkmcnt(6)
	v_mov_b32_e32 v61, v68
	s_waitcnt lgkmcnt(5)
	v_mov_b32_e32 v62, v64
	s_waitcnt lgkmcnt(4)
	v_mov_b32_e32 v63, v70
	v_pk_mul_f32 v[60:61], v[2:3], v[60:61]
	v_pk_mul_f32 v[62:63], v[4:5], v[62:63]
	v_mov_b32_e32 v68, v67
	v_mov_b32_e32 v70, v65
	v_cvt_pk_bf16_f32 v60, v60, v61
	v_cvt_pk_bf16_f32 v61, v62, v63
	s_waitcnt lgkmcnt(3)
	v_mov_b32_e32 v62, v72
	s_waitcnt lgkmcnt(2)
	v_mov_b32_e32 v63, v74
	s_waitcnt lgkmcnt(1)
	v_mov_b32_e32 v80, v76
	s_waitcnt lgkmcnt(0)
	v_mov_b32_e32 v81, v78
	v_pk_mul_f32 v[2:3], v[2:3], v[68:69]
	v_pk_mul_f32 v[4:5], v[4:5], v[70:71]
	v_mov_b32_e32 v74, v73
	v_mov_b32_e32 v78, v77
	v_pk_mul_f32 v[62:63], v[6:7], v[62:63]
	v_pk_mul_f32 v[80:81], v[8:9], v[80:81]
	v_cvt_pk_bf16_f32 v2, v2, v3
	v_cvt_pk_bf16_f32 v3, v4, v5
	v_pk_mul_f32 v[4:5], v[6:7], v[74:75]
	v_pk_mul_f32 v[6:7], v[8:9], v[78:79]
	v_cvt_pk_bf16_f32 v62, v62, v63
	v_cvt_pk_bf16_f32 v63, v80, v81
	v_or_b32_e32 v80, s10, v26
	v_cvt_pk_bf16_f32 v4, v4, v5
	v_cvt_pk_bf16_f32 v5, v6, v7
	v_or_b32_e32 v6, s10, v27
	v_ashrrev_i32_e32 v81, 31, v80
	v_ashrrev_i32_e32 v7, 31, v6
	v_lshlrev_b64 v[80:81], 12, v[80:81]
	v_lshlrev_b64 v[6:7], 12, v[6:7]
	v_lshl_add_u64 v[80:81], v[16:17], 0, v[80:81]
	v_lshl_add_u64 v[6:7], v[16:17], 0, v[6:7]
	global_store_dwordx4 v[80:81], v[60:63], off sc1
	global_store_dwordx4 v[6:7], v[2:5], off sc1
	s_waitcnt lgkmcnt(0)

; __device__ __forceinline__ void transpose_item(const float* W, int K, int N, bf16* WT, int k0, int n0, int dst_row0, const float* gain_k0, float* scr, int lane) {
;     ...
;     const float* src = W + (size_t)(k0 + r) * N + n0 + 4 * q;
;     f32x4 v[16];
; #pragma unroll
;     for (int i = 0; i < 16; ++i) v[i] = __builtin_nontemporal_load((const f32x4*)(src + (size_t)(4 * i) * N));
; #pragma unroll
;     for (int i = 0; i < 16; ++i) { float* d = scr + (4 * i + r) * 65 + 4 * q; d[0] = v[i].x; d[1] = v[i].y; d[2] = v[i].z; d[3] = v[i].w; }
;     asm volatile("s_waitcnt lgkmcnt(0)" ::: "memory");
; __device__ __forceinline__ void convert_items(const Args& A, unsigned char* ws, int g0, int g1, int w, int nw, float* scr, int lane) {
;     for (int it = g0 + w; it < g1; it += nw) {
;         const int l = it / PER_LAYER; int r = it % PER_LAYER;
;         if (r < I_IN) { const int nb = INW / 64, kb = r / nb, n0 = 64 * (r % nb); transpose_item(A.w_in + (size_t)l * DM * INW, DM, INW, (bf16*)(ws + WS_WIN + l * SZ_WIN), 64 * kb, n0, n0, A.norm1_g + l * DM + 64 * kb, scr, lane); continue; } r -= I_IN;
;         if (r < I_OUT) { const int nb = DM / 64, kb = r / nb, n0 = 64 * (r % nb); transpose_item(A.w_out + (size_t)l * DM * DM, DM, DM, (bf16*)(ws + WS_WOUT + l * SZ_WOUT), 64 * kb, n0, n0, (kb < 16 ? A.out_norm_a + l * 1024 + 64 * kb : A.out_norm_b + l * 1024 + 64 * (kb - 16)), scr, lane); continue; } r -= I_OUT;
;         if (r < I_G) { const int nb = DFF / 64, kb = r / nb, n0 = 64 * (r % nb); transpose_item(A.w_gate + (size_t)l * DM * DFF, DM, DFF, (bf16*)(ws + WS_WGU + l * SZ_WGU), 64 * kb, n0, 256 * (n0 / 128) + (n0 % 128), A.norm2_g + l * DM + 64 * kb, scr, lane); continue; } r -= I_G;
;         if (r < I_G) { const int nb = DFF / 64, kb = r / nb, n0 = 64 * (r % nb); transpose_item(A.w_up + (size_t)l * DM * DFF, DM, DFF, (bf16*)(ws + WS_WGU + l * SZ_WGU), 64 * kb, n0, 256 * (n0 / 128) + 128 + (n0 % 128), A.norm2_g + l * DM + 64 * kb, scr, lane); continue; } r -= I_G;
;         { const int nb = DM / 64, kb = r / nb, n0 = 64 * (r % nb); transpose_item(A.w_down + (size_t)l * DFF * DM, DFF, DM, (bf16*)(ws + WS_WDN + l * SZ_WDN), 64 * kb, n0, n0, nullptr, scr, lane); }
.LBB0_11:
	s_mul_hi_i32 s0, s67, 0x2e8ba2e9
	s_lshr_b32 s8, s0, 31
	s_ashr_i32 s0, s0, 11
	s_add_i32 s8, s0, s8
	s_mul_i32 s0, s8, 0xffffd400
	s_add_i32 s12, s67, s0
	s_cmpk_gt_i32 s12, 0x6ff
	s_mov_b64 s[10:11], -1
	s_cbranch_scc0 .LBB0_34
	s_cmpk_gt_u32 s12, 0xaff
	s_cbranch_scc0 .LBB0_28
	s_cmpk_gt_u32 s12, 0x15ff
	s_cbranch_scc0 .LBB0_22
	s_cmpk_gt_u32 s12, 0x20ff
	s_cbranch_scc0 .LBB0_16
	s_and_b32 s9, s28, 0x7c0
	s_mul_i32 s10, s8, 0x2c00000
	v_readlane_b32 s68, v250, 1
	s_mul_hi_i32 s0, s8, 0x2c00000
	v_readlane_b32 s69, v250, 2
	s_add_u32 s68, s68, s10
	s_addc_u32 s69, s69, s0
	s_mul_i32 s10, s8, 0x1600000
	v_readlane_b32 s70, v250, 3
	s_mul_hi_i32 s0, s8, 0x1600000
	s_add_u32 s13, s20, s10
	s_addc_u32 s70, s21, s0
	s_mul_i32 s0, s8, 0xffffa800
	s_add_i32 s0, s34, s0
	s_and_b32 s0, s0, 0x7fffffc0
	s_add_i32 s10, s0, 0xffffbe00
	v_or_b32_e32 v2, s10, v13
	v_mov_b32_e32 v3, v11
	v_lshlrev_b64 v[2:3], 13, v[2:3]
	v_lshl_add_u64 v[2:3], s[68:69], 0, v[2:3]
	s_lshl_b32 s0, s9, 2
	v_lshl_add_u64 v[2:3], v[2:3], 0, s[0:1]
	v_lshl_add_u64 v[16:17], v[2:3], 0, v[10:11]
	v_add_co_u32_e32 v6, vcc, s75, v16
	s_mov_b32 s11, s1
	s_nop 0
	v_addc_co_u32_e32 v7, vcc, 0, v17, vcc
	v_add_co_u32_e32 v60, vcc, s76, v16
	global_load_dwordx4 v[2:5], v[16:17], off nt
	s_nop 0
	global_load_dwordx4 v[6:9], v[6:7], off nt
	v_addc_co_u32_e32 v61, vcc, 0, v17, vcc
	v_add_co_u32_e32 v64, vcc, s77, v16
	s_lshl_b64 s[10:11], s[10:11], 1
	s_nop 0
	v_addc_co_u32_e32 v65, vcc, 0, v17, vcc
	v_add_co_u32_e32 v68, vcc, s78, v16
	global_load_dwordx4 v[60:63], v[60:61], off nt
	s_nop 0
	global_load_dwordx4 v[64:67], v[64:65], off nt
	v_addc_co_u32_e32 v69, vcc, 0, v17, vcc
	v_add_co_u32_e32 v72, vcc, s79, v16
	s_add_u32 s10, s13, s10
	s_nop 0
	v_addc_co_u32_e32 v73, vcc, 0, v17, vcc
	v_add_co_u32_e32 v76, vcc, s80, v16
	global_load_dwordx4 v[68:71], v[68:69], off nt
	s_nop 0
	global_load_dwordx4 v[72:75], v[72:73], off nt
	v_addc_co_u32_e32 v77, vcc, 0, v17, vcc
	v_add_co_u32_e32 v80, vcc, s81, v16
	s_addc_u32 s11, s70, s11
	s_nop 0
	v_addc_co_u32_e32 v81, vcc, 0, v17, vcc
	v_add_co_u32_e32 v84, vcc, s82, v16
	global_load_dwordx4 v[76:79], v[76:77], off nt
	s_nop 0
	global_load_dwordx4 v[80:83], v[80:81], off nt
	v_addc_co_u32_e32 v85, vcc, 0, v17, vcc
	v_add_co_u32_e32 v88, vcc, s83, v16
	v_mov_b32_e32 v15, v11
	s_nop 0
	v_addc_co_u32_e32 v89, vcc, 0, v17, vcc
	v_add_co_u32_e32 v92, vcc, s87, v16
	global_load_dwordx4 v[84:87], v[84:85], off nt
	s_nop 0
	global_load_dwordx4 v[88:91], v[88:89], off nt
	v_addc_co_u32_e32 v93, vcc, 0, v17, vcc
	v_add_co_u32_e32 v96, vcc, s88, v16
	v_readlane_b32 s71, v250, 4
	s_nop 0
	v_addc_co_u32_e32 v97, vcc, 0, v17, vcc
	v_add_co_u32_e32 v100, vcc, s89, v16
	global_load_dwordx4 v[92:95], v[92:93], off nt
	s_nop 0
	global_load_dwordx4 v[96:99], v[96:97], off nt
	v_addc_co_u32_e32 v101, vcc, 0, v17, vcc
	v_add_co_u32_e32 v104, vcc, s90, v16
	s_nop 1
	v_addc_co_u32_e32 v105, vcc, 0, v17, vcc
	global_load_dwordx4 v[100:103], v[100:101], off nt
	s_nop 0
	global_load_dwordx4 v[104:107], v[104:105], off nt
	v_add_co_u32_e32 v108, vcc, s91, v16
	s_nop 1
	v_addc_co_u32_e32 v109, vcc, 0, v17, vcc
	global_load_dwordx4 v[108:111], v[108:109], off nt
	v_add_co_u32_e32 v16, vcc, s52, v16
	s_nop 1
	v_addc_co_u32_e32 v17, vcc, 0, v17, vcc
	global_load_dwordx4 v[112:115], v[16:17], off nt
	s_waitcnt vmcnt(15)
	ds_write2_b32 v18, v2, v3 offset1:1
	ds_write2_b32 v18, v4, v5 offset0:2 offset1:3
	s_waitcnt vmcnt(14)
	ds_write2_b32 v28, v6, v7 offset1:1
	ds_write2_b32 v29, v8, v9 offset1:1
	s_waitcnt vmcnt(13)
	ds_write2_b32 v30, v60, v61 offset1:1
	ds_write2_b32 v31, v62, v63 offset1:1
	s_waitcnt vmcnt(12)
	ds_write2_b32 v32, v64, v65 offset1:1
	ds_write2_b32 v33, v66, v67 offset1:1
	s_waitcnt vmcnt(11)
	ds_write2_b32 v34, v68, v69 offset1:1
	ds_write2_b32 v35, v70, v71 offset1:1
	s_waitcnt vmcnt(10)
	ds_write2_b32 v36, v72, v73 offset1:1
	ds_write2_b32 v37, v74, v75 offset1:1
	s_waitcnt vmcnt(9)
	ds_write2_b32 v38, v76, v77 offset1:1
	ds_write2_b32 v39, v78, v79 offset1:1
	s_waitcnt vmcnt(8)
	ds_write2_b32 v40, v80, v81 offset1:1
	ds_write2_b32 v41, v82, v83 offset1:1
	s_waitcnt vmcnt(7)
	ds_write2_b32 v42, v84, v85 offset1:1
	ds_write2_b32 v43, v86, v87 offset1:1
	s_waitcnt vmcnt(6)
	ds_write2_b32 v44, v88, v89 offset1:1
	ds_write2_b32 v45, v90, v91 offset1:1
	s_waitcnt vmcnt(5)
	ds_write2_b32 v46, v92, v93 offset1:1
	ds_write2_b32 v47, v94, v95 offset1:1
	s_waitcnt vmcnt(4)
	ds_write2_b32 v48, v96, v97 offset1:1
	ds_write2_b32 v49, v98, v99 offset1:1
	s_waitcnt vmcnt(3)
	ds_write2_b32 v50, v100, v101 offset1:1
	ds_write2_b32 v51, v102, v103 offset1:1
	s_waitcnt vmcnt(2)
	ds_write2_b32 v52, v104, v105 offset1:1
	ds_write2_b32 v53, v106, v107 offset1:1
	s_waitcnt vmcnt(1)
	ds_write2_b32 v54, v108, v109 offset1:1
	ds_write2_b32 v55, v110, v111 offset1:1
	s_waitcnt vmcnt(0)
; __device__ __forceinline__ unsigned pkbf(float lo, float hi) { typedef float f2_t __attribute__((ext_vector_type(2))); typedef __bf16 b2_t __attribute__((ext_vector_type(2))); f2_t v = {lo, hi}; b2_t b = __builtin_convertvector(v, b2_t); return __builtin_bit_cast(unsigned, b); }
; __device__ __forceinline__ void transpose_item(const float* W, int K, int N, bf16* WT, int k0, int n0, int dst_row0, const float* gain_k0, float* scr, int lane) {
;     ...
;     asm volatile("s_waitcnt lgkmcnt(0)" ::: "memory");
;     const int c = lane & 7;
;     f32x4 g0 = (f32x4){1.f, 1.f, 1.f, 1.f}, g1 = g0;
;     if (gain_k0) { g0 = *(const f32x4*)(gain_k0 + 8 * c); g1 = *(const f32x4*)(gain_k0 + 8 * c + 4); }
; #pragma unroll
;     for (int j = 0; j < 8; ++j) { const int n = (lane >> 3) + 8 * j; const float* s = scr + (8 * c) * 65 + n;
;         u32x4 o; o.x = pkbf(s[0 * 65] * g0.x, s[1 * 65] * g0.y); o.y = pkbf(s[2 * 65] * g0.z, s[3 * 65] * g0.w); o.z = pkbf(s[4 * 65] * g1.x, s[5 * 65] * g1.y); o.w = pkbf(s[6 * 65] * g1.z, s[7 * 65] * g1.w);
;         *(u32x4*)(WT + (size_t)(dst_row0 + n) * K + k0 + 8 * c) = o; }
;     asm volatile("s_waitcnt lgkmcnt(0)" ::: "memory");
; __device__ __forceinline__ void convert_items(const Args& A, unsigned char* ws, int g0, int g1, int w, int nw, float* scr, int lane) {
;     ...
;         { const int nb = DM / 64, kb = r / nb, n0 = 64 * (r % nb); transpose_item(A.w_down + (size_t)l * DFF * DM, DFF, DM, (bf16*)(ws + WS_WDN + l * SZ_WDN), 64 * kb, n0, n0, nullptr, scr, lane); }
	ds_write2_b32 v56, v112, v113 offset1:1
	ds_write2_b32 v57, v114, v115 offset1:1
	s_waitcnt lgkmcnt(0)
	ds_read2_b32 v[6:7], v20 offset0:65 offset1:73
	ds_read2_b32 v[8:9], v20 offset1:8
	ds_read2_b32 v[16:17], v20 offset0:130 offset1:138
	ds_read2_b32 v[60:61], v20 offset0:195 offset1:203
	ds_read2_b32 v[62:63], v58 offset0:4 offset1:12
	ds_read2_b32 v[64:65], v58 offset0:69 offset1:77
	ds_read2_b32 v[66:67], v58 offset0:134 offset1:142
	ds_read2_b32 v[68:69], v58 offset0:199 offset1:207
	s_waitcnt lgkmcnt(6)
	v_cvt_pk_bf16_f32 v2, v8, v6
	v_or_b32_e32 v6, s9, v19
	v_mul_u32_u24_e32 v6, 0x1600, v6
	v_lshl_add_u64 v[70:71], s[10:11], 0, v[14:15]
	v_lshlrev_b32_e32 v72, 1, v6
	v_mov_b32_e32 v73, v11
	s_waitcnt lgkmcnt(4)
	v_cvt_pk_bf16_f32 v3, v16, v60
	s_waitcnt lgkmcnt(2)
	v_cvt_pk_bf16_f32 v4, v62, v64
	s_waitcnt lgkmcnt(0)
	v_cvt_pk_bf16_f32 v5, v66, v68
	v_lshl_add_u64 v[72:73], v[70:71], 0, v[72:73]
	v_or_b32_e32 v6, s9, v21
	global_store_dwordx4 v[72:73], v[2:5], off sc1
	v_mul_u32_u24_e32 v6, 0x1600, v6
	v_lshlrev_b32_e32 v6, 1, v6
	v_cvt_pk_bf16_f32 v2, v9, v7
	v_cvt_pk_bf16_f32 v3, v17, v61
	v_cvt_pk_bf16_f32 v4, v63, v65
	v_cvt_pk_bf16_f32 v5, v67, v69
	v_mov_b32_e32 v7, v11
	ds_read2_b32 v[8:9], v20 offset0:16 offset1:24
	ds_read2_b32 v[16:17], v20 offset0:81 offset1:89
	ds_read2_b32 v[60:61], v20 offset0:146 offset1:154
	ds_read2_b32 v[62:63], v20 offset0:211 offset1:219
	ds_read2_b32 v[64:65], v58 offset0:20 offset1:28
	ds_read2_b32 v[66:67], v58 offset0:85 offset1:93
	ds_read2_b32 v[68:69], v58 offset0:150 offset1:158
	ds_read2_b32 v[72:73], v58 offset0:215 offset1:223
	v_lshl_add_u64 v[6:7], v[70:71], 0, v[6:7]
	global_store_dwordx4 v[6:7], v[2:5], off sc1
	v_or_b32_e32 v6, s9, v22
	v_mul_u32_u24_e32 v6, 0x1600, v6
	v_lshlrev_b32_e32 v6, 1, v6
	v_mov_b32_e32 v7, v11
	s_waitcnt lgkmcnt(6)
	v_cvt_pk_bf16_f32 v2, v8, v16
	s_waitcnt lgkmcnt(4)
	v_cvt_pk_bf16_f32 v3, v60, v62
	s_waitcnt lgkmcnt(2)
	v_cvt_pk_bf16_f32 v4, v64, v66
	s_waitcnt lgkmcnt(0)
	v_cvt_pk_bf16_f32 v5, v68, v72
	v_lshl_add_u64 v[6:7], v[70:71], 0, v[6:7]
	global_store_dwordx4 v[6:7], v[2:5], off sc1
	v_or_b32_e32 v6, s9, v23
	v_mul_u32_u24_e32 v6, 0x1600, v6
	v_cvt_pk_bf16_f32 v2, v9, v17
	v_cvt_pk_bf16_f32 v3, v61, v63
	v_cvt_pk_bf16_f32 v4, v65, v67
	v_cvt_pk_bf16_f32 v5, v69, v73
	v_lshlrev_b32_e32 v6, 1, v6
	v_mov_b32_e32 v7, v11
	ds_read2_b32 v[8:9], v20 offset0:32 offset1:40
	ds_read2_b32 v[16:17], v20 offset0:97 offset1:105
	ds_read2_b32 v[60:61], v20 offset0:162 offset1:170
	ds_read2_b32 v[62:63], v20 offset0:227 offset1:235
	ds_read2_b32 v[64:65], v58 offset0:36 offset1:44
	ds_read2_b32 v[66:67], v58 offset0:101 offset1:109
	ds_read2_b32 v[68:69], v58 offset0:166 offset1:174
	ds_read2_b32 v[72:73], v58 offset0:231 offset1:239
	v_lshl_add_u64 v[6:7], v[70:71], 0, v[6:7]
	global_store_dwordx4 v[6:7], v[2:5], off sc1
	v_or_b32_e32 v6, s9, v24
	v_mul_u32_u24_e32 v6, 0x1600, v6
	v_lshlrev_b32_e32 v6, 1, v6
	v_mov_b32_e32 v7, v11
	s_waitcnt lgkmcnt(6)
	v_cvt_pk_bf16_f32 v2, v8, v16
	s_waitcnt lgkmcnt(4)
	v_cvt_pk_bf16_f32 v3, v60, v62
	s_waitcnt lgkmcnt(2)
	v_cvt_pk_bf16_f32 v4, v64, v66
	s_waitcnt lgkmcnt(0)
	v_cvt_pk_bf16_f32 v5, v68, v72
	v_lshl_add_u64 v[6:7], v[70:71], 0, v[6:7]
	global_store_dwordx4 v[6:7], v[2:5], off sc1
	v_or_b32_e32 v6, s9, v25
	v_mul_u32_u24_e32 v6, 0x1600, v6
	v_cvt_pk_bf16_f32 v2, v9, v17
	v_cvt_pk_bf16_f32 v3, v61, v63
	v_cvt_pk_bf16_f32 v4, v65, v67
	v_cvt_pk_bf16_f32 v5, v69, v73
	v_lshlrev_b32_e32 v6, 1, v6
	v_mov_b32_e32 v7, v11
	ds_read2_b32 v[8:9], v20 offset0:48 offset1:56
	ds_read2_b32 v[16:17], v20 offset0:113 offset1:121
	ds_read2_b32 v[60:61], v20 offset0:178 offset1:186
	ds_read2_b32 v[62:63], v20 offset0:243 offset1:251
	ds_read2_b32 v[64:65], v58 offset0:52 offset1:60
	ds_read2_b32 v[66:67], v58 offset0:117 offset1:125
	ds_read2_b32 v[68:69], v58 offset0:182 offset1:190
	ds_read2_b32 v[72:73], v58 offset0:247 offset1:255
	v_lshl_add_u64 v[6:7], v[70:71], 0, v[6:7]
	global_store_dwordx4 v[6:7], v[2:5], off sc1
	v_or_b32_e32 v6, s9, v26
	v_mul_u32_u24_e32 v6, 0x1600, v6
	v_lshlrev_b32_e32 v6, 1, v6
	v_mov_b32_e32 v7, v11
	s_waitcnt lgkmcnt(6)
	v_cvt_pk_bf16_f32 v2, v8, v16
	s_waitcnt lgkmcnt(4)
	v_cvt_pk_bf16_f32 v3, v60, v62
	s_waitcnt lgkmcnt(2)
	v_cvt_pk_bf16_f32 v4, v64, v66
	s_waitcnt lgkmcnt(0)
	v_cvt_pk_bf16_f32 v5, v68, v72
	v_lshl_add_u64 v[6:7], v[70:71], 0, v[6:7]
	global_store_dwordx4 v[6:7], v[2:5], off sc1
	v_or_b32_e32 v6, s9, v27
	v_mul_u32_u24_e32 v6, 0x1600, v6
	v_lshlrev_b32_e32 v6, 1, v6
	v_mov_b32_e32 v7, v11
	v_cvt_pk_bf16_f32 v2, v9, v17
	v_cvt_pk_bf16_f32 v3, v61, v63
	v_cvt_pk_bf16_f32 v4, v65, v67
	v_cvt_pk_bf16_f32 v5, v69, v73
	v_lshl_add_u64 v[6:7], v[70:71], 0, v[6:7]
	global_store_dwordx4 v[6:7], v[2:5], off sc1
	s_waitcnt lgkmcnt(0)
	s_mov_b64 s[10:11], 0

; __device__ __forceinline__ unsigned pkbf(float lo, float hi) { typedef float f2_t __attribute__((ext_vector_type(2))); typedef __bf16 b2_t __attribute__((ext_vector_type(2))); f2_t v = {lo, hi}; b2_t b = __builtin_convertvector(v, b2_t); return __builtin_bit_cast(unsigned, b); }
; __device__ __forceinline__ void transpose_item(const float* W, int K, int N, bf16* WT, int k0, int n0, int dst_row0, const float* gain_k0, float* scr, int lane) {
;     ...
; #pragma unroll
;     for (int j = 0; j < 8; ++j) { const int n = (lane >> 3) + 8 * j; const float* s = scr + (8 * c) * 65 + n;
;         u32x4 o; o.x = pkbf(s[0 * 65] * g0.x, s[1 * 65] * g0.y); o.y = pkbf(s[2 * 65] * g0.z, s[3 * 65] * g0.w); o.z = pkbf(s[4 * 65] * g1.x, s[5 * 65] * g1.y); o.w = pkbf(s[6 * 65] * g1.z, s[7 * 65] * g1.w);
;         *(u32x4*)(WT + (size_t)(dst_row0 + n) * K + k0 + 8 * c) = o; }
;     asm volatile("s_waitcnt lgkmcnt(0)" ::: "memory");
; __device__ __forceinline__ void convert_items(const Args& A, unsigned char* ws, int g0, int g1, int w, int nw, float* scr, int lane) {
;     ...
;         if (r < I_G) { const int nb = DFF / 64, kb = r / nb, n0 = 64 * (r % nb); transpose_item(A.w_up + (size_t)l * DM * DFF, DM, DFF, (bf16*)(ws + WS_WGU + l * SZ_WGU), 64 * kb, n0, 256 * (n0 / 128) + 128 + (n0 % 128), A.norm2_g + l * DM + 64 * kb, scr, lane); continue; } r -= I_G;
.LBB0_20:
	ds_read2_b32 v[64:65], v20 offset1:8
	ds_read2_b32 v[66:67], v20 offset0:65 offset1:73
	ds_read2_b32 v[68:69], v20 offset0:130 offset1:138
	ds_read2_b32 v[70:71], v20 offset0:195 offset1:203
	s_lshl_b32 s0, s9, 6
	s_add_u32 s10, s22, s68
	ds_read2_b32 v[72:73], v58 offset0:4 offset1:12
	ds_read2_b32 v[74:75], v58 offset0:69 offset1:77
	ds_read2_b32 v[76:77], v58 offset0:134 offset1:142
	ds_read2_b32 v[78:79], v58 offset0:199 offset1:207
	s_addc_u32 s11, s23, s13
	s_lshl_b32 s9, s9, 7
	s_and_b32 s0, s0, 64
	s_or_b32 s0, s0, s9
	s_bitset1_b32 s0, 7
	s_lshl_b32 s9, s69, 1
	s_waitcnt lgkmcnt(7)
	v_mov_b32_e32 v60, v64
	s_waitcnt lgkmcnt(6)
	v_mov_b32_e32 v61, v66
	s_waitcnt lgkmcnt(5)
	v_mov_b32_e32 v62, v68
	s_waitcnt lgkmcnt(4)
	v_mov_b32_e32 v63, v70
	s_add_u32 s10, s10, s9
	s_waitcnt vmcnt(1)
	v_pk_mul_f32 v[60:61], v[6:7], v[60:61]
	v_pk_mul_f32 v[62:63], v[8:9], v[62:63]
	s_addc_u32 s11, s11, 0
	v_mov_b32_e32 v15, v11
	v_cvt_pk_bf16_f32 v60, v60, v61
	v_cvt_pk_bf16_f32 v61, v62, v63
	s_waitcnt lgkmcnt(3)
	v_mov_b32_e32 v62, v72
	s_waitcnt lgkmcnt(2)
	v_mov_b32_e32 v63, v74
	s_waitcnt lgkmcnt(1)
	v_mov_b32_e32 v80, v76
	s_waitcnt lgkmcnt(0)
	v_mov_b32_e32 v81, v78
	v_lshl_add_u64 v[16:17], s[10:11], 0, v[14:15]
	s_waitcnt vmcnt(0)
	v_pk_mul_f32 v[62:63], v[2:3], v[62:63]
	v_pk_mul_f32 v[80:81], v[4:5], v[80:81]
	v_or_b32_e32 v15, s0, v19
	v_cvt_pk_bf16_f32 v62, v62, v63
	v_cvt_pk_bf16_f32 v63, v80, v81
	v_lshlrev_b32_e32 v80, 12, v15
	v_mov_b32_e32 v81, v11
	v_lshl_add_u64 v[80:81], v[16:17], 0, v[80:81]
	v_mov_b32_e32 v66, v65
	v_mov_b32_e32 v70, v69
	global_store_dwordx4 v[80:81], v[60:63], off sc1
	v_mov_b32_e32 v74, v73
	v_mov_b32_e32 v78, v77
	v_pk_mul_f32 v[60:61], v[6:7], v[66:67]
	v_pk_mul_f32 v[62:63], v[8:9], v[70:71]
	v_cvt_pk_bf16_f32 v60, v60, v61
	v_cvt_pk_bf16_f32 v61, v62, v63
	v_pk_mul_f32 v[62:63], v[2:3], v[74:75]
	v_pk_mul_f32 v[64:65], v[4:5], v[78:79]
	v_or_b32_e32 v15, s0, v21
	v_cvt_pk_bf16_f32 v62, v62, v63
	v_cvt_pk_bf16_f32 v63, v64, v65
	v_lshlrev_b32_e32 v64, 12, v15
	v_mov_b32_e32 v65, v11
	v_lshl_add_u64 v[64:65], v[16:17], 0, v[64:65]
	ds_read2_b32 v[66:67], v20 offset0:16 offset1:24
	ds_read2_b32 v[68:69], v20 offset0:81 offset1:89
	global_store_dwordx4 v[64:65], v[60:63], off sc1
	ds_read2_b32 v[64:65], v20 offset0:146 offset1:154
	ds_read2_b32 v[70:71], v20 offset0:211 offset1:219
	ds_read2_b32 v[72:73], v58 offset0:20 offset1:28
	ds_read2_b32 v[74:75], v58 offset0:85 offset1:93
	ds_read2_b32 v[76:77], v58 offset0:150 offset1:158
	ds_read2_b32 v[78:79], v58 offset0:215 offset1:223
	s_waitcnt lgkmcnt(7)
	v_mov_b32_e32 v60, v66
	s_waitcnt lgkmcnt(6)
	v_mov_b32_e32 v61, v68
	s_waitcnt lgkmcnt(5)
	v_mov_b32_e32 v62, v64
	s_waitcnt lgkmcnt(4)
	v_mov_b32_e32 v63, v70
	v_pk_mul_f32 v[60:61], v[6:7], v[60:61]
	v_pk_mul_f32 v[62:63], v[8:9], v[62:63]
	v_cvt_pk_bf16_f32 v60, v60, v61
	v_cvt_pk_bf16_f32 v61, v62, v63
	s_waitcnt lgkmcnt(3)
	v_mov_b32_e32 v62, v72
	s_waitcnt lgkmcnt(2)
	v_mov_b32_e32 v63, v74
	s_waitcnt lgkmcnt(1)
	v_mov_b32_e32 v80, v76
	s_waitcnt lgkmcnt(0)
	v_mov_b32_e32 v81, v78
	v_pk_mul_f32 v[62:63], v[2:3], v[62:63]
	v_pk_mul_f32 v[80:81], v[4:5], v[80:81]
	v_or_b32_e32 v15, s0, v22
	v_cvt_pk_bf16_f32 v62, v62, v63
	v_cvt_pk_bf16_f32 v63, v80, v81
	v_lshlrev_b32_e32 v80, 12, v15
	v_mov_b32_e32 v81, v11
	v_lshl_add_u64 v[80:81], v[16:17], 0, v[80:81]
	v_mov_b32_e32 v68, v67
	v_mov_b32_e32 v70, v65
	global_store_dwordx4 v[80:81], v[60:63], off sc1
	v_mov_b32_e32 v74, v73
	v_mov_b32_e32 v78, v77
	v_pk_mul_f32 v[60:61], v[6:7], v[68:69]
	v_pk_mul_f32 v[62:63], v[8:9], v[70:71]
	v_cvt_pk_bf16_f32 v60, v60, v61
	v_cvt_pk_bf16_f32 v61, v62, v63
	v_pk_mul_f32 v[62:63], v[2:3], v[74:75]
	v_pk_mul_f32 v[64:65], v[4:5], v[78:79]
	v_or_b32_e32 v15, s0, v23
	v_cvt_pk_bf16_f32 v62, v62, v63
	v_cvt_pk_bf16_f32 v63, v64, v65
	v_lshlrev_b32_e32 v64, 12, v15
	v_mov_b32_e32 v65, v11
	v_lshl_add_u64 v[64:65], v[16:17], 0, v[64:65]
	ds_read2_b32 v[66:67], v20 offset0:32 offset1:40
	ds_read2_b32 v[68:69], v20 offset0:97 offset1:105
	global_store_dwordx4 v[64:65], v[60:63], off sc1
	ds_read2_b32 v[64:65], v20 offset0:162 offset1:170
	ds_read2_b32 v[70:71], v20 offset0:227 offset1:235
	ds_read2_b32 v[72:73], v58 offset0:36 offset1:44
	ds_read2_b32 v[74:75], v58 offset0:101 offset1:109
	ds_read2_b32 v[76:77], v58 offset0:166 offset1:174
	ds_read2_b32 v[78:79], v58 offset0:231 offset1:239
	s_waitcnt lgkmcnt(7)
; __device__ __forceinline__ unsigned pkbf(float lo, float hi) { typedef float f2_t __attribute__((ext_vector_type(2))); typedef __bf16 b2_t __attribute__((ext_vector_type(2))); f2_t v = {lo, hi}; b2_t b = __builtin_convertvector(v, b2_t); return __builtin_bit_cast(unsigned, b); }
; __device__ __forceinline__ void transpose_item(const float* W, int K, int N, bf16* WT, int k0, int n0, int dst_row0, const float* gain_k0, float* scr, int lane) {
;     ...
; #pragma unroll
;     for (int j = 0; j < 8; ++j) { const int n = (lane >> 3) + 8 * j; const float* s = scr + (8 * c) * 65 + n;
;         u32x4 o; o.x = pkbf(s[0 * 65] * g0.x, s[1 * 65] * g0.y); o.y = pkbf(s[2 * 65] * g0.z, s[3 * 65] * g0.w); o.z = pkbf(s[4 * 65] * g1.x, s[5 * 65] * g1.y); o.w = pkbf(s[6 * 65] * g1.z, s[7 * 65] * g1.w);
;         *(u32x4*)(WT + (size_t)(dst_row0 + n) * K + k0 + 8 * c) = o; }
;     asm volatile("s_waitcnt lgkmcnt(0)" ::: "memory");
	v_mov_b32_e32 v60, v66
	s_waitcnt lgkmcnt(6)
	v_mov_b32_e32 v61, v68
	s_waitcnt lgkmcnt(5)
	v_mov_b32_e32 v62, v64
	s_waitcnt lgkmcnt(4)
	v_mov_b32_e32 v63, v70
	v_pk_mul_f32 v[60:61], v[6:7], v[60:61]
	v_pk_mul_f32 v[62:63], v[8:9], v[62:63]
	v_cvt_pk_bf16_f32 v60, v60, v61
	v_cvt_pk_bf16_f32 v61, v62, v63
	s_waitcnt lgkmcnt(3)
	v_mov_b32_e32 v62, v72
	s_waitcnt lgkmcnt(2)
	v_mov_b32_e32 v63, v74
	s_waitcnt lgkmcnt(1)
	v_mov_b32_e32 v80, v76
	s_waitcnt lgkmcnt(0)
	v_mov_b32_e32 v81, v78
	v_pk_mul_f32 v[62:63], v[2:3], v[62:63]
	v_pk_mul_f32 v[80:81], v[4:5], v[80:81]
	v_or_b32_e32 v15, s0, v24
	v_cvt_pk_bf16_f32 v62, v62, v63
	v_cvt_pk_bf16_f32 v63, v80, v81
	v_lshlrev_b32_e32 v80, 12, v15
	v_mov_b32_e32 v81, v11
	v_lshl_add_u64 v[80:81], v[16:17], 0, v[80:81]
	v_mov_b32_e32 v68, v67
	v_mov_b32_e32 v70, v65
	global_store_dwordx4 v[80:81], v[60:63], off sc1
	v_mov_b32_e32 v74, v73
	v_mov_b32_e32 v78, v77
	v_pk_mul_f32 v[60:61], v[6:7], v[68:69]
	v_pk_mul_f32 v[62:63], v[8:9], v[70:71]
	v_cvt_pk_bf16_f32 v60, v60, v61
	v_cvt_pk_bf16_f32 v61, v62, v63
	v_pk_mul_f32 v[62:63], v[2:3], v[74:75]
	v_pk_mul_f32 v[64:65], v[4:5], v[78:79]
	v_or_b32_e32 v15, s0, v25
	v_cvt_pk_bf16_f32 v62, v62, v63
	v_cvt_pk_bf16_f32 v63, v64, v65
	v_lshlrev_b32_e32 v64, 12, v15
	v_mov_b32_e32 v65, v11
	v_lshl_add_u64 v[64:65], v[16:17], 0, v[64:65]
	ds_read2_b32 v[66:67], v20 offset0:48 offset1:56
	ds_read2_b32 v[68:69], v20 offset0:113 offset1:121
	global_store_dwordx4 v[64:65], v[60:63], off sc1
	ds_read2_b32 v[64:65], v20 offset0:178 offset1:186
	ds_read2_b32 v[70:71], v20 offset0:243 offset1:251
	ds_read2_b32 v[72:73], v58 offset0:52 offset1:60
	ds_read2_b32 v[74:75], v58 offset0:117 offset1:125
	ds_read2_b32 v[76:77], v58 offset0:182 offset1:190
	ds_read2_b32 v[78:79], v58 offset0:247 offset1:255
	s_waitcnt lgkmcnt(7)
	v_mov_b32_e32 v60, v66
	s_waitcnt lgkmcnt(6)
	v_mov_b32_e32 v61, v68
	s_waitcnt lgkmcnt(5)
	v_mov_b32_e32 v62, v64
	s_waitcnt lgkmcnt(4)
	v_mov_b32_e32 v63, v70
	v_pk_mul_f32 v[60:61], v[6:7], v[60:61]
	v_pk_mul_f32 v[62:63], v[8:9], v[62:63]
	v_cvt_pk_bf16_f32 v60, v60, v61
	v_cvt_pk_bf16_f32 v61, v62, v63
	s_waitcnt lgkmcnt(3)
	v_mov_b32_e32 v62, v72
	s_waitcnt lgkmcnt(2)
	v_mov_b32_e32 v63, v74
	v_mov_b32_e32 v68, v67
	v_mov_b32_e32 v70, v65
	v_mov_b32_e32 v74, v73
	v_pk_mul_f32 v[62:63], v[2:3], v[62:63]
	s_waitcnt lgkmcnt(0)
	v_mov_b32_e32 v81, v78
	v_pk_mul_f32 v[6:7], v[6:7], v[68:69]
	v_pk_mul_f32 v[8:9], v[8:9], v[70:71]
	v_pk_mul_f32 v[2:3], v[2:3], v[74:75]
	v_mov_b32_e32 v78, v77
	v_mov_b32_e32 v80, v76
	v_cvt_pk_bf16_f32 v6, v6, v7
	v_cvt_pk_bf16_f32 v7, v8, v9
	v_cvt_pk_bf16_f32 v8, v2, v3
	v_pk_mul_f32 v[2:3], v[4:5], v[78:79]
	v_pk_mul_f32 v[80:81], v[4:5], v[80:81]
	v_or_b32_e32 v15, s0, v26
	v_cvt_pk_bf16_f32 v9, v2, v3
	v_or_b32_e32 v2, s0, v27
	v_cvt_pk_bf16_f32 v62, v62, v63
	v_cvt_pk_bf16_f32 v63, v80, v81
	v_lshlrev_b32_e32 v80, 12, v15
	v_mov_b32_e32 v81, v11
	v_lshlrev_b32_e32 v2, 12, v2
	v_mov_b32_e32 v3, v11
	v_lshl_add_u64 v[80:81], v[16:17], 0, v[80:81]
	v_lshl_add_u64 v[2:3], v[16:17], 0, v[2:3]
	global_store_dwordx4 v[80:81], v[60:63], off sc1
	global_store_dwordx4 v[2:3], v[6:9], off sc1
	s_waitcnt lgkmcnt(0)

; __device__ __forceinline__ unsigned pkbf(float lo, float hi) { typedef float f2_t __attribute__((ext_vector_type(2))); typedef __bf16 b2_t __attribute__((ext_vector_type(2))); f2_t v = {lo, hi}; b2_t b = __builtin_convertvector(v, b2_t); return __builtin_bit_cast(unsigned, b); }
; __device__ __forceinline__ void transpose_item(const float* W, int K, int N, bf16* WT, int k0, int n0, int dst_row0, const float* gain_k0, float* scr, int lane) {
;     ...
; #pragma unroll
;     for (int j = 0; j < 8; ++j) { const int n = (lane >> 3) + 8 * j; const float* s = scr + (8 * c) * 65 + n;
;         u32x4 o; o.x = pkbf(s[0 * 65] * g0.x, s[1 * 65] * g0.y); o.y = pkbf(s[2 * 65] * g0.z, s[3 * 65] * g0.w); o.z = pkbf(s[4 * 65] * g1.x, s[5 * 65] * g1.y); o.w = pkbf(s[6 * 65] * g1.z, s[7 * 65] * g1.w);
;         *(u32x4*)(WT + (size_t)(dst_row0 + n) * K + k0 + 8 * c) = o; }
;     asm volatile("s_waitcnt lgkmcnt(0)" ::: "memory");
; __device__ __forceinline__ void convert_items(const Args& A, unsigned char* ws, int g0, int g1, int w, int nw, float* scr, int lane) {
;     ...
;         if (r < I_G) { const int nb = DFF / 64, kb = r / nb, n0 = 64 * (r % nb); transpose_item(A.w_gate + (size_t)l * DM * DFF, DM, DFF, (bf16*)(ws + WS_WGU + l * SZ_WGU), 64 * kb, n0, 256 * (n0 / 128) + (n0 % 128), A.norm2_g + l * DM + 64 * kb, scr, lane); continue; } r -= I_G;
.LBB0_26:
	ds_read2_b32 v[64:65], v20 offset1:8
	ds_read2_b32 v[66:67], v20 offset0:65 offset1:73
	ds_read2_b32 v[68:69], v20 offset0:130 offset1:138
	ds_read2_b32 v[70:71], v20 offset0:195 offset1:203
	s_lshl_b32 s0, s9, 6
	s_add_u32 s10, s22, s68
	ds_read2_b32 v[72:73], v58 offset0:4 offset1:12
	ds_read2_b32 v[74:75], v58 offset0:69 offset1:77
	ds_read2_b32 v[76:77], v58 offset0:134 offset1:142
	ds_read2_b32 v[78:79], v58 offset0:199 offset1:207
	s_addc_u32 s11, s23, s13
	s_lshl_b32 s9, s9, 7
	s_and_b32 s9, s9, 0x3f00
	s_and_b32 s0, s0, 64
	s_or_b32 s0, s9, s0
	s_lshl_b32 s9, s69, 1
	s_waitcnt lgkmcnt(7)
	v_mov_b32_e32 v60, v64
	s_waitcnt lgkmcnt(6)
	v_mov_b32_e32 v61, v66
	s_waitcnt lgkmcnt(5)
	v_mov_b32_e32 v62, v68
	s_waitcnt lgkmcnt(4)
	v_mov_b32_e32 v63, v70
	s_add_u32 s10, s10, s9
	s_waitcnt vmcnt(1)
	v_pk_mul_f32 v[60:61], v[6:7], v[60:61]
	v_pk_mul_f32 v[62:63], v[8:9], v[62:63]
	s_addc_u32 s11, s11, 0
	v_mov_b32_e32 v15, v11
	v_cvt_pk_bf16_f32 v60, v60, v61
	v_cvt_pk_bf16_f32 v61, v62, v63
	s_waitcnt lgkmcnt(3)
	v_mov_b32_e32 v62, v72
	s_waitcnt lgkmcnt(2)
	v_mov_b32_e32 v63, v74
	s_waitcnt lgkmcnt(1)
	v_mov_b32_e32 v80, v76
	s_waitcnt lgkmcnt(0)
	v_mov_b32_e32 v81, v78
	v_lshl_add_u64 v[16:17], s[10:11], 0, v[14:15]
	s_waitcnt vmcnt(0)
	v_pk_mul_f32 v[62:63], v[2:3], v[62:63]
	v_pk_mul_f32 v[80:81], v[4:5], v[80:81]
	v_or_b32_e32 v15, s0, v19
	v_cvt_pk_bf16_f32 v62, v62, v63
	v_cvt_pk_bf16_f32 v63, v80, v81
	v_lshlrev_b32_e32 v80, 12, v15
	v_mov_b32_e32 v81, v11
	v_lshl_add_u64 v[80:81], v[16:17], 0, v[80:81]
	v_mov_b32_e32 v66, v65
	v_mov_b32_e32 v70, v69
	global_store_dwordx4 v[80:81], v[60:63], off sc1
	v_mov_b32_e32 v74, v73
	v_mov_b32_e32 v78, v77
	v_pk_mul_f32 v[60:61], v[6:7], v[66:67]
	v_pk_mul_f32 v[62:63], v[8:9], v[70:71]
	v_cvt_pk_bf16_f32 v60, v60, v61
	v_cvt_pk_bf16_f32 v61, v62, v63
	v_pk_mul_f32 v[62:63], v[2:3], v[74:75]
	v_pk_mul_f32 v[64:65], v[4:5], v[78:79]
	v_or_b32_e32 v15, s0, v21
	v_cvt_pk_bf16_f32 v62, v62, v63
	v_cvt_pk_bf16_f32 v63, v64, v65
	v_lshlrev_b32_e32 v64, 12, v15
	v_mov_b32_e32 v65, v11
	v_lshl_add_u64 v[64:65], v[16:17], 0, v[64:65]
	ds_read2_b32 v[66:67], v20 offset0:16 offset1:24
	ds_read2_b32 v[68:69], v20 offset0:81 offset1:89
	global_store_dwordx4 v[64:65], v[60:63], off sc1
	ds_read2_b32 v[64:65], v20 offset0:146 offset1:154
	ds_read2_b32 v[70:71], v20 offset0:211 offset1:219
	ds_read2_b32 v[72:73], v58 offset0:20 offset1:28
	ds_read2_b32 v[74:75], v58 offset0:85 offset1:93
	ds_read2_b32 v[76:77], v58 offset0:150 offset1:158
	ds_read2_b32 v[78:79], v58 offset0:215 offset1:223
	s_waitcnt lgkmcnt(7)
	v_mov_b32_e32 v60, v66
	s_waitcnt lgkmcnt(6)
	v_mov_b32_e32 v61, v68
	s_waitcnt lgkmcnt(5)
	v_mov_b32_e32 v62, v64
	s_waitcnt lgkmcnt(4)
	v_mov_b32_e32 v63, v70
	v_pk_mul_f32 v[60:61], v[6:7], v[60:61]
	v_pk_mul_f32 v[62:63], v[8:9], v[62:63]
	v_cvt_pk_bf16_f32 v60, v60, v61
	v_cvt_pk_bf16_f32 v61, v62, v63
	s_waitcnt lgkmcnt(3)
	v_mov_b32_e32 v62, v72
	s_waitcnt lgkmcnt(2)
	v_mov_b32_e32 v63, v74
	s_waitcnt lgkmcnt(1)
	v_mov_b32_e32 v80, v76
	s_waitcnt lgkmcnt(0)
	v_mov_b32_e32 v81, v78
	v_pk_mul_f32 v[62:63], v[2:3], v[62:63]
	v_pk_mul_f32 v[80:81], v[4:5], v[80:81]
	v_or_b32_e32 v15, s0, v22
	v_cvt_pk_bf16_f32 v62, v62, v63
	v_cvt_pk_bf16_f32 v63, v80, v81
	v_lshlrev_b32_e32 v80, 12, v15
	v_mov_b32_e32 v81, v11
	v_lshl_add_u64 v[80:81], v[16:17], 0, v[80:81]
	v_mov_b32_e32 v68, v67
	v_mov_b32_e32 v70, v65
	global_store_dwordx4 v[80:81], v[60:63], off sc1
	v_mov_b32_e32 v74, v73
	v_mov_b32_e32 v78, v77
	v_pk_mul_f32 v[60:61], v[6:7], v[68:69]
	v_pk_mul_f32 v[62:63], v[8:9], v[70:71]
	v_cvt_pk_bf16_f32 v60, v60, v61
	v_cvt_pk_bf16_f32 v61, v62, v63
	v_pk_mul_f32 v[62:63], v[2:3], v[74:75]
	v_pk_mul_f32 v[64:65], v[4:5], v[78:79]
	v_or_b32_e32 v15, s0, v23
	v_cvt_pk_bf16_f32 v62, v62, v63
	v_cvt_pk_bf16_f32 v63, v64, v65
	v_lshlrev_b32_e32 v64, 12, v15
	v_mov_b32_e32 v65, v11
	v_lshl_add_u64 v[64:65], v[16:17], 0, v[64:65]
	ds_read2_b32 v[66:67], v20 offset0:32 offset1:40
	ds_read2_b32 v[68:69], v20 offset0:97 offset1:105
	global_store_dwordx4 v[64:65], v[60:63], off sc1
	ds_read2_b32 v[64:65], v20 offset0:162 offset1:170
	ds_read2_b32 v[70:71], v20 offset0:227 offset1:235
	ds_read2_b32 v[72:73], v58 offset0:36 offset1:44
	ds_read2_b32 v[74:75], v58 offset0:101 offset1:109
	ds_read2_b32 v[76:77], v58 offset0:166 offset1:174
	ds_read2_b32 v[78:79], v58 offset0:231 offset1:239
	s_waitcnt lgkmcnt(7)
; __device__ __forceinline__ unsigned pkbf(float lo, float hi) { typedef float f2_t __attribute__((ext_vector_type(2))); typedef __bf16 b2_t __attribute__((ext_vector_type(2))); f2_t v = {lo, hi}; b2_t b = __builtin_convertvector(v, b2_t); return __builtin_bit_cast(unsigned, b); }
; __device__ __forceinline__ void transpose_item(const float* W, int K, int N, bf16* WT, int k0, int n0, int dst_row0, const float* gain_k0, float* scr, int lane) {
;     ...
; #pragma unroll
;     for (int j = 0; j < 8; ++j) { const int n = (lane >> 3) + 8 * j; const float* s = scr + (8 * c) * 65 + n;
;         u32x4 o; o.x = pkbf(s[0 * 65] * g0.x, s[1 * 65] * g0.y); o.y = pkbf(s[2 * 65] * g0.z, s[3 * 65] * g0.w); o.z = pkbf(s[4 * 65] * g1.x, s[5 * 65] * g1.y); o.w = pkbf(s[6 * 65] * g1.z, s[7 * 65] * g1.w);
;         *(u32x4*)(WT + (size_t)(dst_row0 + n) * K + k0 + 8 * c) = o; }
;     asm volatile("s_waitcnt lgkmcnt(0)" ::: "memory");
	v_mov_b32_e32 v60, v66
	s_waitcnt lgkmcnt(6)
	v_mov_b32_e32 v61, v68
	s_waitcnt lgkmcnt(5)
	v_mov_b32_e32 v62, v64
	s_waitcnt lgkmcnt(4)
	v_mov_b32_e32 v63, v70
	v_pk_mul_f32 v[60:61], v[6:7], v[60:61]
	v_pk_mul_f32 v[62:63], v[8:9], v[62:63]
	v_cvt_pk_bf16_f32 v60, v60, v61
	v_cvt_pk_bf16_f32 v61, v62, v63
	s_waitcnt lgkmcnt(3)
	v_mov_b32_e32 v62, v72
	s_waitcnt lgkmcnt(2)
	v_mov_b32_e32 v63, v74
	s_waitcnt lgkmcnt(1)
	v_mov_b32_e32 v80, v76
	s_waitcnt lgkmcnt(0)
	v_mov_b32_e32 v81, v78
	v_pk_mul_f32 v[62:63], v[2:3], v[62:63]
	v_pk_mul_f32 v[80:81], v[4:5], v[80:81]
	v_or_b32_e32 v15, s0, v24
	v_cvt_pk_bf16_f32 v62, v62, v63
	v_cvt_pk_bf16_f32 v63, v80, v81
	v_lshlrev_b32_e32 v80, 12, v15
	v_mov_b32_e32 v81, v11
	v_lshl_add_u64 v[80:81], v[16:17], 0, v[80:81]
	v_mov_b32_e32 v68, v67
	v_mov_b32_e32 v70, v65
	global_store_dwordx4 v[80:81], v[60:63], off sc1
	v_mov_b32_e32 v74, v73
	v_mov_b32_e32 v78, v77
	v_pk_mul_f32 v[60:61], v[6:7], v[68:69]
	v_pk_mul_f32 v[62:63], v[8:9], v[70:71]
	v_cvt_pk_bf16_f32 v60, v60, v61
	v_cvt_pk_bf16_f32 v61, v62, v63
	v_pk_mul_f32 v[62:63], v[2:3], v[74:75]
	v_pk_mul_f32 v[64:65], v[4:5], v[78:79]
	v_or_b32_e32 v15, s0, v25
	v_cvt_pk_bf16_f32 v62, v62, v63
	v_cvt_pk_bf16_f32 v63, v64, v65
	v_lshlrev_b32_e32 v64, 12, v15
	v_mov_b32_e32 v65, v11
	v_lshl_add_u64 v[64:65], v[16:17], 0, v[64:65]
	ds_read2_b32 v[66:67], v20 offset0:48 offset1:56
	ds_read2_b32 v[68:69], v20 offset0:113 offset1:121
	global_store_dwordx4 v[64:65], v[60:63], off sc1
	ds_read2_b32 v[64:65], v20 offset0:178 offset1:186
	ds_read2_b32 v[70:71], v20 offset0:243 offset1:251
	ds_read2_b32 v[72:73], v58 offset0:52 offset1:60
	ds_read2_b32 v[74:75], v58 offset0:117 offset1:125
	ds_read2_b32 v[76:77], v58 offset0:182 offset1:190
	ds_read2_b32 v[78:79], v58 offset0:247 offset1:255
	s_waitcnt lgkmcnt(7)
	v_mov_b32_e32 v60, v66
	s_waitcnt lgkmcnt(6)
	v_mov_b32_e32 v61, v68
	s_waitcnt lgkmcnt(5)
	v_mov_b32_e32 v62, v64
	s_waitcnt lgkmcnt(4)
	v_mov_b32_e32 v63, v70
	v_pk_mul_f32 v[60:61], v[6:7], v[60:61]
	v_pk_mul_f32 v[62:63], v[8:9], v[62:63]
	v_cvt_pk_bf16_f32 v60, v60, v61
	v_cvt_pk_bf16_f32 v61, v62, v63
	s_waitcnt lgkmcnt(3)
	v_mov_b32_e32 v62, v72
	s_waitcnt lgkmcnt(2)
	v_mov_b32_e32 v63, v74
	v_mov_b32_e32 v68, v67
	v_mov_b32_e32 v70, v65
	v_mov_b32_e32 v74, v73
	v_pk_mul_f32 v[62:63], v[2:3], v[62:63]
	s_waitcnt lgkmcnt(0)
	v_mov_b32_e32 v81, v78
	v_pk_mul_f32 v[6:7], v[6:7], v[68:69]
	v_pk_mul_f32 v[8:9], v[8:9], v[70:71]
	v_pk_mul_f32 v[2:3], v[2:3], v[74:75]
	v_mov_b32_e32 v78, v77
	v_mov_b32_e32 v80, v76
	v_cvt_pk_bf16_f32 v6, v6, v7
	v_cvt_pk_bf16_f32 v7, v8, v9
	v_cvt_pk_bf16_f32 v8, v2, v3
	v_pk_mul_f32 v[2:3], v[4:5], v[78:79]
	v_pk_mul_f32 v[80:81], v[4:5], v[80:81]
	v_or_b32_e32 v15, s0, v26
	v_cvt_pk_bf16_f32 v9, v2, v3
	v_or_b32_e32 v2, s0, v27
	v_cvt_pk_bf16_f32 v62, v62, v63
	v_cvt_pk_bf16_f32 v63, v80, v81
	v_lshlrev_b32_e32 v80, 12, v15
	v_mov_b32_e32 v81, v11
	v_lshlrev_b32_e32 v2, 12, v2
	v_mov_b32_e32 v3, v11
	v_lshl_add_u64 v[80:81], v[16:17], 0, v[80:81]
	v_lshl_add_u64 v[2:3], v[16:17], 0, v[2:3]
	global_store_dwordx4 v[80:81], v[60:63], off sc1
	global_store_dwordx4 v[2:3], v[6:9], off sc1
	s_waitcnt lgkmcnt(0)

; __device__ __forceinline__ unsigned pkbf(float lo, float hi) { typedef float f2_t __attribute__((ext_vector_type(2))); typedef __bf16 b2_t __attribute__((ext_vector_type(2))); f2_t v = {lo, hi}; b2_t b = __builtin_convertvector(v, b2_t); return __builtin_bit_cast(unsigned, b); }
; __device__ __forceinline__ void transpose_item(const float* W, int K, int N, bf16* WT, int k0, int n0, int dst_row0, const float* gain_k0, float* scr, int lane) {
;     ...
;     const int c = lane & 7;
;     f32x4 g0 = (f32x4){1.f, 1.f, 1.f, 1.f}, g1 = g0;
;     if (gain_k0) { g0 = *(const f32x4*)(gain_k0 + 8 * c); g1 = *(const f32x4*)(gain_k0 + 8 * c + 4); }
; #pragma unroll
;     for (int j = 0; j < 8; ++j) { const int n = (lane >> 3) + 8 * j; const float* s = scr + (8 * c) * 65 + n;
;         u32x4 o; o.x = pkbf(s[0 * 65] * g0.x, s[1 * 65] * g0.y); o.y = pkbf(s[2 * 65] * g0.z, s[3 * 65] * g0.w); o.z = pkbf(s[4 * 65] * g1.x, s[5 * 65] * g1.y); o.w = pkbf(s[6 * 65] * g1.z, s[7 * 65] * g1.w);
;         *(u32x4*)(WT + (size_t)(dst_row0 + n) * K + k0 + 8 * c) = o; }
.LBB0_32:
	ds_read2_b32 v[64:65], v20 offset1:8
	ds_read2_b32 v[66:67], v20 offset0:65 offset1:73
	ds_read2_b32 v[68:69], v20 offset0:130 offset1:138
	ds_read2_b32 v[70:71], v20 offset0:195 offset1:203
	ds_read2_b32 v[72:73], v58 offset0:4 offset1:12
	ds_read2_b32 v[74:75], v58 offset0:69 offset1:77
	ds_read2_b32 v[76:77], v58 offset0:134 offset1:142
	ds_read2_b32 v[78:79], v58 offset0:199 offset1:207
	s_lshl_b64 s[10:11], s[8:9], 23
	s_add_u32 s9, s24, s10
	s_addc_u32 s11, s25, s11
	s_lshl_b32 s0, s0, 1
	s_waitcnt lgkmcnt(7)
	v_mov_b32_e32 v60, v64
	s_waitcnt lgkmcnt(6)
	v_mov_b32_e32 v61, v66
	s_waitcnt lgkmcnt(5)
	v_mov_b32_e32 v62, v68
	s_waitcnt lgkmcnt(4)
	v_mov_b32_e32 v63, v70
	s_add_u32 s10, s9, s0
	s_waitcnt vmcnt(1)
	v_pk_mul_f32 v[60:61], v[2:3], v[60:61]
	v_pk_mul_f32 v[62:63], v[4:5], v[62:63]
	s_addc_u32 s11, s11, 0
	v_mov_b32_e32 v15, v11
	v_cvt_pk_bf16_f32 v60, v60, v61
	v_cvt_pk_bf16_f32 v61, v62, v63
	s_waitcnt lgkmcnt(3)
	v_mov_b32_e32 v62, v72
	s_waitcnt lgkmcnt(2)
	v_mov_b32_e32 v63, v74
	s_waitcnt lgkmcnt(1)
	v_mov_b32_e32 v80, v76
	s_waitcnt lgkmcnt(0)
	v_mov_b32_e32 v81, v78
	v_lshl_add_u64 v[16:17], s[10:11], 0, v[14:15]
	s_waitcnt vmcnt(0)
	v_pk_mul_f32 v[62:63], v[6:7], v[62:63]
	v_pk_mul_f32 v[80:81], v[8:9], v[80:81]
	v_or_b32_e32 v15, s13, v19
	v_cvt_pk_bf16_f32 v62, v62, v63
	v_cvt_pk_bf16_f32 v63, v80, v81
	v_lshlrev_b32_e32 v80, 12, v15
	v_mov_b32_e32 v81, v11
	v_lshl_add_u64 v[80:81], v[16:17], 0, v[80:81]
	v_mov_b32_e32 v66, v65
	v_mov_b32_e32 v70, v69
	global_store_dwordx4 v[80:81], v[60:63], off sc1
	v_mov_b32_e32 v74, v73
	v_mov_b32_e32 v78, v77
	v_pk_mul_f32 v[60:61], v[2:3], v[66:67]
	v_pk_mul_f32 v[62:63], v[4:5], v[70:71]
	v_cvt_pk_bf16_f32 v60, v60, v61
	v_cvt_pk_bf16_f32 v61, v62, v63
	v_pk_mul_f32 v[62:63], v[6:7], v[74:75]
	v_pk_mul_f32 v[64:65], v[8:9], v[78:79]
	v_or_b32_e32 v15, s13, v21
	v_cvt_pk_bf16_f32 v62, v62, v63
	v_cvt_pk_bf16_f32 v63, v64, v65
	v_lshlrev_b32_e32 v64, 12, v15
	v_mov_b32_e32 v65, v11
	v_lshl_add_u64 v[64:65], v[16:17], 0, v[64:65]
	ds_read2_b32 v[66:67], v20 offset0:16 offset1:24
	ds_read2_b32 v[68:69], v20 offset0:81 offset1:89
	global_store_dwordx4 v[64:65], v[60:63], off sc1
	ds_read2_b32 v[64:65], v20 offset0:146 offset1:154
	ds_read2_b32 v[70:71], v20 offset0:211 offset1:219
	ds_read2_b32 v[72:73], v58 offset0:20 offset1:28
	ds_read2_b32 v[74:75], v58 offset0:85 offset1:93
	ds_read2_b32 v[76:77], v58 offset0:150 offset1:158
	ds_read2_b32 v[78:79], v58 offset0:215 offset1:223
	s_waitcnt lgkmcnt(7)
	v_mov_b32_e32 v60, v66
	s_waitcnt lgkmcnt(6)
	v_mov_b32_e32 v61, v68
	s_waitcnt lgkmcnt(5)
	v_mov_b32_e32 v62, v64
	s_waitcnt lgkmcnt(4)
	v_mov_b32_e32 v63, v70
	v_pk_mul_f32 v[60:61], v[2:3], v[60:61]
	v_pk_mul_f32 v[62:63], v[4:5], v[62:63]
	v_cvt_pk_bf16_f32 v60, v60, v61
	v_cvt_pk_bf16_f32 v61, v62, v63
	s_waitcnt lgkmcnt(3)
	v_mov_b32_e32 v62, v72
	s_waitcnt lgkmcnt(2)
	v_mov_b32_e32 v63, v74
	s_waitcnt lgkmcnt(1)
	v_mov_b32_e32 v80, v76
	s_waitcnt lgkmcnt(0)
	v_mov_b32_e32 v81, v78
	v_pk_mul_f32 v[62:63], v[6:7], v[62:63]
	v_pk_mul_f32 v[80:81], v[8:9], v[80:81]
	v_or_b32_e32 v15, s13, v22
	v_cvt_pk_bf16_f32 v62, v62, v63
	v_cvt_pk_bf16_f32 v63, v80, v81
	v_lshlrev_b32_e32 v80, 12, v15
	v_mov_b32_e32 v81, v11
	v_lshl_add_u64 v[80:81], v[16:17], 0, v[80:81]
	v_mov_b32_e32 v68, v67
	v_mov_b32_e32 v70, v65
	global_store_dwordx4 v[80:81], v[60:63], off sc1
	v_mov_b32_e32 v74, v73
	v_mov_b32_e32 v78, v77
	v_pk_mul_f32 v[60:61], v[2:3], v[68:69]
	v_pk_mul_f32 v[62:63], v[4:5], v[70:71]
	v_cvt_pk_bf16_f32 v60, v60, v61
	v_cvt_pk_bf16_f32 v61, v62, v63
	v_pk_mul_f32 v[62:63], v[6:7], v[74:75]
	v_pk_mul_f32 v[64:65], v[8:9], v[78:79]
	v_or_b32_e32 v15, s13, v23
	v_cvt_pk_bf16_f32 v62, v62, v63
	v_cvt_pk_bf16_f32 v63, v64, v65
	v_lshlrev_b32_e32 v64, 12, v15
	v_mov_b32_e32 v65, v11
	v_lshl_add_u64 v[64:65], v[16:17], 0, v[64:65]
	ds_read2_b32 v[66:67], v20 offset0:32 offset1:40
	ds_read2_b32 v[68:69], v20 offset0:97 offset1:105
	global_store_dwordx4 v[64:65], v[60:63], off sc1
	ds_read2_b32 v[64:65], v20 offset0:162 offset1:170
	ds_read2_b32 v[70:71], v20 offset0:227 offset1:235
	ds_read2_b32 v[72:73], v58 offset0:36 offset1:44
	ds_read2_b32 v[74:75], v58 offset0:101 offset1:109
	ds_read2_b32 v[76:77], v58 offset0:166 offset1:174
	ds_read2_b32 v[78:79], v58 offset0:231 offset1:239
	s_waitcnt lgkmcnt(7)
; __device__ __forceinline__ unsigned pkbf(float lo, float hi) { typedef float f2_t __attribute__((ext_vector_type(2))); typedef __bf16 b2_t __attribute__((ext_vector_type(2))); f2_t v = {lo, hi}; b2_t b = __builtin_convertvector(v, b2_t); return __builtin_bit_cast(unsigned, b); }
; __device__ __forceinline__ void transpose_item(const float* W, int K, int N, bf16* WT, int k0, int n0, int dst_row0, const float* gain_k0, float* scr, int lane) {
;     ...
;     const int c = lane & 7;
;     f32x4 g0 = (f32x4){1.f, 1.f, 1.f, 1.f}, g1 = g0;
;     if (gain_k0) { g0 = *(const f32x4*)(gain_k0 + 8 * c); g1 = *(const f32x4*)(gain_k0 + 8 * c + 4); }
; #pragma unroll
;     for (int j = 0; j < 8; ++j) { const int n = (lane >> 3) + 8 * j; const float* s = scr + (8 * c) * 65 + n;
;         u32x4 o; o.x = pkbf(s[0 * 65] * g0.x, s[1 * 65] * g0.y); o.y = pkbf(s[2 * 65] * g0.z, s[3 * 65] * g0.w); o.z = pkbf(s[4 * 65] * g1.x, s[5 * 65] * g1.y); o.w = pkbf(s[6 * 65] * g1.z, s[7 * 65] * g1.w);
;         *(u32x4*)(WT + (size_t)(dst_row0 + n) * K + k0 + 8 * c) = o; }
	v_mov_b32_e32 v60, v66
	s_waitcnt lgkmcnt(6)
	v_mov_b32_e32 v61, v68
	s_waitcnt lgkmcnt(5)
	v_mov_b32_e32 v62, v64
	s_waitcnt lgkmcnt(4)
	v_mov_b32_e32 v63, v70
	v_pk_mul_f32 v[60:61], v[2:3], v[60:61]
	v_pk_mul_f32 v[62:63], v[4:5], v[62:63]
	v_cvt_pk_bf16_f32 v60, v60, v61
	v_cvt_pk_bf16_f32 v61, v62, v63
	s_waitcnt lgkmcnt(3)
	v_mov_b32_e32 v62, v72
	s_waitcnt lgkmcnt(2)
	v_mov_b32_e32 v63, v74
	s_waitcnt lgkmcnt(1)
	v_mov_b32_e32 v80, v76
	s_waitcnt lgkmcnt(0)
	v_mov_b32_e32 v81, v78
	v_pk_mul_f32 v[62:63], v[6:7], v[62:63]
	v_pk_mul_f32 v[80:81], v[8:9], v[80:81]
	v_or_b32_e32 v15, s13, v24
	v_cvt_pk_bf16_f32 v62, v62, v63
	v_cvt_pk_bf16_f32 v63, v80, v81
	v_lshlrev_b32_e32 v80, 12, v15
	v_mov_b32_e32 v81, v11
	v_lshl_add_u64 v[80:81], v[16:17], 0, v[80:81]
	v_mov_b32_e32 v68, v67
	v_mov_b32_e32 v70, v65
	global_store_dwordx4 v[80:81], v[60:63], off sc1
	v_mov_b32_e32 v74, v73
	v_mov_b32_e32 v78, v77
	v_pk_mul_f32 v[60:61], v[2:3], v[68:69]
	v_pk_mul_f32 v[62:63], v[4:5], v[70:71]
	v_cvt_pk_bf16_f32 v60, v60, v61
	v_cvt_pk_bf16_f32 v61, v62, v63
	v_pk_mul_f32 v[62:63], v[6:7], v[74:75]
	v_pk_mul_f32 v[64:65], v[8:9], v[78:79]
	v_or_b32_e32 v15, s13, v25
	v_cvt_pk_bf16_f32 v62, v62, v63
	v_cvt_pk_bf16_f32 v63, v64, v65
	v_lshlrev_b32_e32 v64, 12, v15
	v_mov_b32_e32 v65, v11
	v_lshl_add_u64 v[64:65], v[16:17], 0, v[64:65]
	ds_read2_b32 v[66:67], v20 offset0:48 offset1:56
	ds_read2_b32 v[68:69], v20 offset0:113 offset1:121
	global_store_dwordx4 v[64:65], v[60:63], off sc1
	ds_read2_b32 v[64:65], v20 offset0:178 offset1:186
	ds_read2_b32 v[70:71], v20 offset0:243 offset1:251
	ds_read2_b32 v[72:73], v58 offset0:52 offset1:60
	ds_read2_b32 v[74:75], v58 offset0:117 offset1:125
	ds_read2_b32 v[76:77], v58 offset0:182 offset1:190
	ds_read2_b32 v[78:79], v58 offset0:247 offset1:255
	s_waitcnt lgkmcnt(7)
	v_mov_b32_e32 v60, v66
	s_waitcnt lgkmcnt(6)
	v_mov_b32_e32 v61, v68
	s_waitcnt lgkmcnt(5)
	v_mov_b32_e32 v62, v64
	s_waitcnt lgkmcnt(4)
	v_mov_b32_e32 v63, v70
	v_pk_mul_f32 v[60:61], v[2:3], v[60:61]
	v_pk_mul_f32 v[62:63], v[4:5], v[62:63]
	v_mov_b32_e32 v68, v67
	v_mov_b32_e32 v70, v65
	v_cvt_pk_bf16_f32 v60, v60, v61
	v_cvt_pk_bf16_f32 v61, v62, v63
	s_waitcnt lgkmcnt(3)
	v_mov_b32_e32 v62, v72
	s_waitcnt lgkmcnt(2)
	v_mov_b32_e32 v63, v74
	s_waitcnt lgkmcnt(0)
	v_mov_b32_e32 v81, v78
	v_pk_mul_f32 v[2:3], v[2:3], v[68:69]
	v_pk_mul_f32 v[4:5], v[4:5], v[70:71]
	v_mov_b32_e32 v74, v73
	v_mov_b32_e32 v78, v77
	v_pk_mul_f32 v[62:63], v[6:7], v[62:63]
	v_mov_b32_e32 v80, v76
	v_cvt_pk_bf16_f32 v2, v2, v3
	v_cvt_pk_bf16_f32 v3, v4, v5
	v_pk_mul_f32 v[4:5], v[6:7], v[74:75]
	v_pk_mul_f32 v[6:7], v[8:9], v[78:79]
	v_pk_mul_f32 v[80:81], v[8:9], v[80:81]
	v_or_b32_e32 v15, s13, v26
	v_cvt_pk_bf16_f32 v4, v4, v5
	v_cvt_pk_bf16_f32 v5, v6, v7
	v_or_b32_e32 v6, s13, v27
	v_cvt_pk_bf16_f32 v62, v62, v63
	v_cvt_pk_bf16_f32 v63, v80, v81
	v_lshlrev_b32_e32 v80, 12, v15
	v_mov_b32_e32 v81, v11
	v_lshlrev_b32_e32 v6, 12, v6
	v_mov_b32_e32 v7, v11
	v_lshl_add_u64 v[80:81], v[16:17], 0, v[80:81]
	v_lshl_add_u64 v[6:7], v[16:17], 0, v[6:7]
	global_store_dwordx4 v[80:81], v[60:63], off sc1
	global_store_dwordx4 v[6:7], v[2:5], off sc1
	s_waitcnt lgkmcnt(0)
